# LDS-DMA attention staging with a scalar tile base (saddr + per-lane 32-bit offsets): no per-tile VALU address updates
# speedup vs baseline: 1.0074x; 1.0074x over previous
.LBB0_218:
	s_bfe_u32 s4, s36, 0x30004
	v_lshl_add_u32 v0, s4, 9, v222
	v_ashrrev_i32_e32 v1, 31, v0
	v_lshl_add_u64 v[0:1], v[0:1], 2, s[14:15]
	global_load_dword v232, v[0:1], off
	s_lshl_b32 s5, s36, 6
	s_and_b32 s66, s5, 0x2000
	s_lshl_b32 s5, s21, 7
	s_add_i32 s5, s5, s58
	s_ashr_i32 s8, s5, 31
	s_add_u32 s62, s5, s66
	s_addc_u32 s63, s8, 0
	v_mov_b32_e32 v1, s63
	s_lshl_b32 s89, s4, 7
	s_lshl_b32 s4, s4, 8
	s_mov_b32 s5, s67
	s_mov_b32 s65, s67
	v_lshl_add_u64 v[2:3], s[66:67], 0, v[146:147]
	v_lshlrev_b64 v[2:3], 10, v[2:3]
	v_mov_b32_e32 v5, v3
	v_add_u32_e32 v20, 0, v159
	s_cmp_eq_u32 s21, 0


	v_or_b32_e32 v0, s62, v144
	v_lshlrev_b64 v[0:1], 11, v[0:1]
	v_lshl_add_u64 v[0:1], s[46:47], 0, v[0:1]
	v_lshl_add_u64 v[0:1], v[0:1], 0, s[4:5]
	v_lshl_add_u64 v[0:1], v[0:1], 0, s[64:65]
	v_lshl_add_u64 v[0:1], v[0:1], 0, v[208:209]
	global_load_dwordx4 v[112:115], v[0:1], off
	global_load_dwordx4 v[116:119], v[0:1], off offset:32
	global_load_dwordx4 v[120:123], v[0:1], off offset:64
	global_load_dwordx4 v[124:127], v[0:1], off offset:96
	s_lshl_b32 s4, s66, 11
	s_lshl_b32 s5, s89, 1
	s_add_u32 s4, s4, s5
	s_add_u32 s80, s10, s4
	s_addc_u32 s81, s11, 0
	s_lshl_b32 s32, s56, 10
	v_lshlrev_b32_e32 v138, 4, v246
	v_mov_b32_e32 v142, 0xf0f0f1
	v_mov_b32_e32 v143, 0xcccccd
	s_movk_i32 s86, 0x110
	s_movk_i32 s87, 0x140
	s_mov_b32 s28, 0x9fe0000
	v_add_u32_e32 v139, s32, v138
	v_mul_hi_u32 v140, v139, v142
	v_mul_lo_u32 v141, v140, s86
	v_sub_u32_e32 v141, v139, v141
	v_cmp_gt_u32_e32 vcc, 0x100, v141
	s_nop 1
	v_cndmask_b32_e32 v141, 0, v141, vcc
	v_lshl_add_u32 v128, v140, 11, v141
	s_add_i32 s65, s32, 0x2000
	v_add_u32_e32 v139, s65, v138
	v_mul_hi_u32 v140, v139, v142
	v_mul_lo_u32 v141, v140, s86
	v_sub_u32_e32 v141, v139, v141
	v_cmp_gt_u32_e32 vcc, 0x100, v141
	s_nop 1
	v_cndmask_b32_e32 v141, 0, v141, vcc
	v_lshl_add_u32 v129, v140, 11, v141
	v_add_u32_e32 v139, s32, v138
	v_mul_hi_u32 v140, v139, v143
	v_mul_lo_u32 v141, v140, s87
	v_sub_u32_e32 v141, v139, v141
	v_cmp_gt_u32_e32 vcc, 0x100, v141
	s_nop 1
	v_cndmask_b32_e32 v141, 0, v141, vcc
	v_lshl_add_u32 v130, v140, 11, v141
	v_add_u32_e32 v130, s28, v130
	v_add_u32_e32 v139, s65, v138
	v_mul_hi_u32 v140, v139, v143
	v_mul_lo_u32 v141, v140, s87
	v_sub_u32_e32 v141, v139, v141
	v_cmp_gt_u32_e32 vcc, 0x100, v141
	s_nop 1
	v_cndmask_b32_e32 v141, 0, v141, vcc
	v_lshl_add_u32 v131, v140, 11, v141
	v_add_u32_e32 v131, s28, v131
	s_add_i32 s65, s32, 0x3c00
	s_cmp_eq_u32 s56, 0
	s_cselect_b32 s65, 0x4000, s65
	s_cselect_b32 s86, s86, s87
	s_mov_b32 s87, 0xcccccd
	s_cselect_b32 s87, 0xf0f0f1, s87
	s_cselect_b32 s28, 0, s28
	v_add_u32_e32 v139, s65, v138
	v_mul_hi_u32 v140, v139, s87
	v_mul_lo_u32 v141, v140, s86
	v_sub_u32_e32 v141, v139, v141
	v_cmp_gt_u32_e32 vcc, 0x100, v141
	s_nop 1
	v_cndmask_b32_e32 v141, 0, v141, vcc
	v_lshl_add_u32 v132, v140, 11, v141
	v_add_u32_e32 v132, s28, v132
	s_mov_b32 s28, 0
	s_add_i32 m0, s28, s32
	s_nop 0
	global_load_lds_dwordx4 v128, s[80:81]
	s_add_i32 m0, m0, 0x2000
	s_nop 0
	global_load_lds_dwordx4 v129, s[80:81]
	s_cmp_eq_u32 s56, 0
	s_cbranch_scc0 .Ldk_p0
	s_add_i32 m0, s28, 0x4000
	s_nop 0
	global_load_lds_dwordx4 v132, s[80:81]
.Ldk_p0:
	s_add_u32 s80, s80, 0x20000
	s_addc_u32 s81, s81, 0
	s_mov_b32 s29, 0x8800
	s_add_i32 m0, s29, s32
	s_nop 0
	global_load_lds_dwordx4 v130, s[80:81]
	s_add_i32 m0, m0, 0x2000
	s_nop 0
	global_load_lds_dwordx4 v131, s[80:81]
	s_cmp_eq_u32 s56, 0
	s_cbranch_scc1 .Ldv_p0
	s_cmp_gt_u32 s56, 4
	s_cbranch_scc1 .Ldv_p0
	s_add_i32 m0, s29, s32
	s_add_i32 m0, m0, 0x3c00
	s_nop 0
	global_load_lds_dwordx4 v132, s[80:81]
.Ldv_p0:
	s_movk_i32 s28, 0x4400
	s_add_i32 m0, s28, s32
	s_nop 0
	global_load_lds_dwordx4 v128, s[80:81]
	s_add_i32 m0, m0, 0x2000
	s_nop 0
	global_load_lds_dwordx4 v129, s[80:81]
	s_cmp_eq_u32 s56, 0
	s_cbranch_scc0 .Ldk_p1
	s_add_i32 m0, s28, 0x4000
	s_nop 0
	global_load_lds_dwordx4 v132, s[80:81]
.Ldk_p1:
	s_add_u32 s80, s80, 0x20000
	s_addc_u32 s81, s81, 0
	s_mov_b32 s29, 0xd800
	s_add_i32 m0, s29, s32
	s_nop 0
	global_load_lds_dwordx4 v130, s[80:81]
	s_add_i32 m0, m0, 0x2000
	s_nop 0
	global_load_lds_dwordx4 v131, s[80:81]
	s_cmp_eq_u32 s56, 0
	s_cbranch_scc1 .Ldv_p1
	s_cmp_gt_u32 s56, 4
	s_cbranch_scc1 .Ldv_p1
	s_add_i32 m0, s29, s32
	s_add_i32 m0, m0, 0x3c00
	s_nop 0
	global_load_lds_dwordx4 v132, s[80:81]
.Ldv_p1:
	s_cmp_eq_u32 s21, 0
	s_cbranch_scc1 .Lpro_nk2
	s_mov_b32 s28, 0x20400
	s_add_i32 m0, s28, s32
	s_nop 0
	global_load_lds_dwordx4 v128, s[80:81]
	s_add_i32 m0, m0, 0x2000
	s_nop 0
	global_load_lds_dwordx4 v129, s[80:81]
	s_cmp_eq_u32 s56, 0
	s_cbranch_scc0 .Ldk_p2
	s_add_i32 m0, s28, 0x4000
	s_nop 0
	global_load_lds_dwordx4 v132, s[80:81]
.Ldk_p2:
.Lpro_nk2:
	s_add_u32 s80, s80, 0x20000
	s_addc_u32 s81, s81, 0
	s_waitcnt vmcnt(0)
	ds_write_b32 v149, v232
	s_waitcnt lgkmcnt(0)
	s_barrier



.LBB0_227:
	s_lshl_b32 s4, s59, 11
	s_and_b32 s5, s4, 0x1000000
	s_lshl_b32 s4, s36, 4
	s_and_b32 s28, s4, 0x700
	v_lshl_or_b32 v96, v148, 1, s28
	v_or_b32_e32 v96, s5, v96
	v_mov_b32_e32 v97, v209
	s_lshl_b32 s21, s21, 9
	s_mov_b32 s65, 2
	s_add_i32 s66, s8, 2
	s_mov_b32 s4, 1
	v_lshl_add_u64 v[174:175], v[170:171], 0, v[96:97]
	v_subrev_u32_e32 v204, s21, v194
	s_add_i32 s33, s61, s8
	s_mov_b32 s87, 0
	s_movk_i32 s68, 0xff00
	s_waitcnt lgkmcnt(0)
	s_barrier
	s_and_b64 vcc, exec, s[16:17]
	s_cbranch_vccz .Latt_p_qk
	s_cmp_ge_u32 s65, s66
	s_cbranch_scc1 .LBB0_228
	s_mov_b32 s5, 0
	s_mov_b32 s28, 0x12800
	s_add_i32 m0, s5, s32
	s_nop 0
	global_load_lds_dwordx4 v128, s[80:81]
	s_add_i32 m0, m0, 0x2000
	s_nop 0
	global_load_lds_dwordx4 v129, s[80:81]
	s_cmp_eq_u32 s56, 0
	s_cbranch_scc0 .Ldk_p3
	s_add_i32 m0, s5, 0x4000
	s_nop 0
	global_load_lds_dwordx4 v132, s[80:81]
.Ldk_p3:
	s_add_i32 m0, s28, s32
	s_nop 0
	global_load_lds_dwordx4 v130, s[80:81]
	s_add_i32 m0, m0, 0x2000
	s_nop 0
	global_load_lds_dwordx4 v131, s[80:81]
	s_cmp_eq_u32 s56, 0
	s_cbranch_scc1 .Ldv_p3
	s_cmp_gt_u32 s56, 4
	s_cbranch_scc1 .Ldv_p3
	s_add_i32 m0, s28, s32
	s_add_i32 m0, m0, 0x3c00
	s_nop 0
	global_load_lds_dwordx4 v132, s[80:81]
.Ldv_p3:
	s_add_u32 s80, s80, 0x20000
	s_addc_u32 s81, s81, 0
	s_branch .LBB0_228

.LBB0_228:
	s_add_i32 s86, s65, -1
	s_bitcmp0_b32 s86, 0
	s_mov_b32 s69, s4
	s_mov_b32 s28, 0x20400
	s_cmp_eq_u32 s69, 0
	s_cselect_b32 s28, 0x4400, s28
	s_cmp_eq_u32 s69, 2
	s_cselect_b32 s28, 0, s28
	s_mul_i32 s5, s69, 0x4400
	s_cselect_b32 s5, 0x20400, s5
	s_mul_i32 s29, s69, 0x5000
	s_addk_i32 s29, 0x5000
	s_cmp_lg_u32 s69, 2
	s_cselect_b32 s29, s29, 0
	s_and_b64 vcc, exec, s[16:17]
	s_cbranch_vccnz .Latt_a
	s_cmp_ge_u32 s65, s66
	s_cbranch_scc1 .Latt_b_nod
	s_add_i32 s4, s65, 1
	s_cmp_ge_u32 s4, s66
	s_cbranch_scc1 .Latt_b_nok
	s_sub_i32 s4, 0x24800, s5
	s_sub_i32 s4, s4, s28
	s_add_i32 m0, s4, s32
	s_nop 0
	global_load_lds_dwordx4 v128, s[80:81]
	s_add_i32 m0, m0, 0x2000
	s_nop 0
	global_load_lds_dwordx4 v129, s[80:81]
	s_cmp_eq_u32 s56, 0
	s_cbranch_scc0 .Ldk_b
	s_add_i32 m0, s4, 0x4000
	s_nop 0
	global_load_lds_dwordx4 v132, s[80:81]
.Ldk_b:
.Latt_b_nok:
	s_add_i32 s4, s29, 0x8800
	s_add_i32 m0, s4, s32
	s_nop 0
	global_load_lds_dwordx4 v130, s[80:81]
	s_add_i32 m0, m0, 0x2000
	s_nop 0
	global_load_lds_dwordx4 v131, s[80:81]
	s_cmp_eq_u32 s56, 0
	s_cbranch_scc1 .Ldv_b
	s_cmp_gt_u32 s56, 4
	s_cbranch_scc1 .Ldv_b
	s_add_i32 m0, s4, s32
	s_add_i32 m0, m0, 0x3c00
	s_nop 0
	global_load_lds_dwordx4 v132, s[80:81]
.Ldv_b:
	s_add_u32 s80, s80, 0x20000
	s_addc_u32 s81, s81, 0

.Lwd_a:
	s_barrier
	s_add_i32 s4, s65, 1
	s_cmp_ge_u32 s4, s66
	s_cbranch_scc1 .Latt_a_nod
	s_add_i32 s4, s65, 2
	s_cmp_ge_u32 s4, s66
	s_cbranch_scc1 .Latt_a_nok
	s_add_i32 m0, s5, s32
	s_nop 0
	global_load_lds_dwordx4 v128, s[80:81]
	s_add_i32 m0, m0, 0x2000
	s_nop 0
	global_load_lds_dwordx4 v129, s[80:81]
	s_cmp_eq_u32 s56, 0
	s_cbranch_scc0 .Ldk_a
	s_add_i32 m0, s5, 0x4000
	s_nop 0
	global_load_lds_dwordx4 v132, s[80:81]
.Ldk_a:
.Latt_a_nok:
	s_mul_i32 s29, s87, 0x5000
	s_add_i32 s29, s29, 0x8800
	s_add_i32 m0, s29, s32
	s_nop 0
	global_load_lds_dwordx4 v130, s[80:81]
	s_add_i32 m0, m0, 0x2000
	s_nop 0
	global_load_lds_dwordx4 v131, s[80:81]
	s_cmp_eq_u32 s56, 0
	s_cbranch_scc1 .Ldv_a
	s_cmp_gt_u32 s56, 4
	s_cbranch_scc1 .Ldv_a
	s_add_i32 m0, s29, s32
	s_add_i32 m0, m0, 0x3c00
	s_nop 0
	global_load_lds_dwordx4 v132, s[80:81]
